# v29 + per-unit tile decode: second integer division (group size always 8) replaced by shift/mask
# baseline (speedup 1.0000x reference)
;     __host__ __device__ bool next(int i, Unit& u) const {
;         const long L = (long)i * G + c; if (L >= nwg) return false;
;         int wgid = (int)L; { const int q = nwg / NXCD, r = nwg % NXCD, xcd = wgid % NXCD, off = wgid / NXCD; wgid = (xcd < r ? xcd * (q + 1) : r * (q + 1) + (xcd - r) * q) + off; }
;         const int nig = WGM * nN, gid = wgid / nig, fm = gid * WGM, gsz = (nM - fm) < WGM ? (nM - fm) : WGM;
;         u.pm = fm + ((wgid % nig) % gsz); u.pn = (wgid % nig) / gsz; return true;
;     }
.LBB0_298:
	s_add_i32 s79, s79, 1
	s_mul_i32 s4, s79, s7
	s_mul_hi_u32 s5, s79, s92
	s_add_i32 s5, s5, s4
	s_mul_i32 s4, s79, s92
	s_add_u32 s8, s4, s2
	s_addc_u32 s9, s5, s55
	v_mov_b64_e32 v[0:1], s[20:21]
	v_cmp_ge_i64_e32 vcc, s[8:9], v[0:1]
	v_cmp_lt_i64_e64 s[10:11], s[8:9], v[0:1]
	s_cbranch_vccnz .LBB0_300
	s_ashr_i32 s4, s8, 31
	s_lshr_b32 s4, s4, 29
	s_add_i32 s4, s8, s4
	s_ashr_i32 s5, s4, 3
	s_and_b32 s4, s4, -8
	s_sub_i32 s4, s8, s4
	s_lshr_b32 s8, s4, 31
	s_or_b32 s8, s8, s81
	s_mul_i32 s4, s8, s4
	s_add_i32 s4, s4, s5
	s_abs_i32 s8, s4
	s_mul_hi_u32 s9, s8, s84
	s_mul_i32 s30, s9, s83
	s_ashr_i32 s5, s4, 31
	s_sub_i32 s8, s8, s30
	s_xor_b32 s5, s5, s59
	s_add_i32 s30, s9, 1
	s_sub_i32 s31, s8, s83
	s_cmp_ge_u32 s8, s83
	s_cselect_b32 s9, s30, s9
	s_cselect_b32 s8, s31, s8
	s_add_i32 s30, s9, 1
	s_cmp_ge_u32 s8, s83
	s_cselect_b32 s8, s30, s9
	s_xor_b32 s8, s8, s5
	s_sub_i32 s5, s8, s5
	s_lshl_b32 s8, s5, 3
	s_sub_i32 s9, 0x80, s8
	s_min_i32 s9, s9, 8
	s_mul_i32 s5, s5, s82
	s_sub_i32 s4, s4, s5
	s_lshr_b32 s85, s4, 3
	s_and_b32 s4, s4, 7
	s_add_i32 s86, s4, s8
